# v119 + the s81 write moved from the per-tile heads into per-parity hand-over stubs
# baseline (speedup 1.0000x reference)
; #define ATT_LAS __attribute__((address_space(3)))
; __device__ __forceinline__ int sub1(int a) { int v = a ^ 128; asm volatile("" : "+v"(v)); return v; }
; #define ATT_MFMA(a, b, c) __builtin_amdgcn_mfma_f32_32x32x16_bf16((a), (b), (c), 0, 0, 0)
; #define ATT_STAGE(t, buf) do { _Pragma("unroll") for (int i_ = 0; i_ < 2; ++i_) { \
;         glds16(Kt + (size_t)(t) * 131072, ksrc[i_], (unsigned)__builtin_amdgcn_readfirstlane(ldsb + KBUF + (buf) * 16384 + (w * 2 + i_) * 1024)); \
;         glds16(Vt + (size_t)(t) * 131072, vsrc[i_], (unsigned)__builtin_amdgcn_readfirstlane(ldsb + VBUF + (buf) * 16384 + (w * 2 + i_) * 1024)); } } while (0)
; template <bool C1> __device__ __forceinline__ void qk_issue(f32x16& s0, const ATT_LAS unsigned char* kb, const ATT_LAS unsigned char* qb_, const int (&kaddr)[4]) {
; #pragma unroll
;     for (int i = 0; i < 16; ++i) s0[i] = 0.f;
; #pragma unroll
;     for (int ds = 0; ds < 4; ++ds) {
;         const int ad = C1 ? sub1(kaddr[ds]) : kaddr[ds];
;         const bf16x8 a0 = *(const ATT_LAS bf16x8*)(kb + ad);
;         const bf16x8 qv = *(const ATT_LAS bf16x8*)(qb_ + ad);
;         s0 = ATT_MFMA(a0, qv, s0);
;     }
; }
; __device__ __forceinline__ void attn_unit(ATT_LAS unsigned char* lds, const bf16_t* Qg, const bf16_t* Kg, const bf16_t* Vg, bf16_t* Og, int b, int head, int qb, float lam, const float* subg) {
;     ...
;     for (int t = 0; t < NT; ++t) {
;         const int buf = t & 1;
;         if (t + 1 < NT) ATT_STAGE(t + 1, buf ^ 1);
;         const int kvrel = 64 * t - q0 - 32 * wq;
;         if (kvrel <= 31) {
;             const ATT_LAS unsigned char* kb = lds + KBUF + buf * 16384;
;             const ATT_LAS unsigned char* vb = lds + VBUF + buf * 16384;
;             tile_body(kvrel + 63 > 0, kb, vb, qbase, kaddr, vaddr, O1, O2, m1, m2, l1, l2, kvrel, r, h, wsf);
.Lhead_p0:
	s_add_i32 s79, s79, 1
	s_add_i32 m0, s77, 0x4000
	s_cmp_ge_u32 s79, s76
	s_cbranch_scc1 .Lq_prefetch_p0
	global_load_lds_dwordx4 v198, s[92:93]
.Ltile_p0:
	s_cmp_gt_i32 s80, 31
	s_cbranch_scc1 .Ldma_skip
.Lbody_p0:
	ds_read_b128 v[2:5], v203
	ds_read_b128 v[6:9], v217
	ds_read_b128 v[10:13], v204
	ds_read_b128 v[146:149], v219
	ds_read_b128 v[150:153], v205
	ds_read_b128 v[154:157], v221
	ds_read_b128 v[158:161], v206
	ds_read_b128 v[162:165], v223
	s_cmpk_gt_i32 s80, 0xffc1
	s_cselect_b64 s[36:37], -1, 0
	s_cmpk_lt_i32 s80, 0xffc2
	s_waitcnt lgkmcnt(4)
	v_mfma_f32_32x32x16_bf16 v[170:185], v[2:5], v[6:9], 0
	v_mfma_f32_32x32x16_bf16 v[170:185], v[10:13], v[146:149], v[170:185]
	s_waitcnt lgkmcnt(0)
	v_mfma_f32_32x32x16_bf16 v[170:185], v[150:153], v[154:157], v[170:185]
	v_mfma_f32_32x32x16_bf16 v[170:185], v[158:161], v[162:165], v[170:185]
	s_cbranch_scc0 .Lhead_mask_p0

; #define ATT_LAS __attribute__((address_space(3)))
; __device__ __forceinline__ int sub1(int a) { int v = a ^ 128; asm volatile("" : "+v"(v)); return v; }
; #define ATT_MFMA(a, b, c) __builtin_amdgcn_mfma_f32_32x32x16_bf16((a), (b), (c), 0, 0, 0)
; #define ATT_STAGE(t, buf) do { _Pragma("unroll") for (int i_ = 0; i_ < 2; ++i_) { \
;         glds16(Kt + (size_t)(t) * 131072, ksrc[i_], (unsigned)__builtin_amdgcn_readfirstlane(ldsb + KBUF + (buf) * 16384 + (w * 2 + i_) * 1024)); \
;         glds16(Vt + (size_t)(t) * 131072, vsrc[i_], (unsigned)__builtin_amdgcn_readfirstlane(ldsb + VBUF + (buf) * 16384 + (w * 2 + i_) * 1024)); } } while (0)
; template <bool C1> __device__ __forceinline__ void qk_issue(f32x16& s0, const ATT_LAS unsigned char* kb, const ATT_LAS unsigned char* qb_, const int (&kaddr)[4]) {
; #pragma unroll
;     for (int i = 0; i < 16; ++i) s0[i] = 0.f;
; #pragma unroll
;     for (int ds = 0; ds < 4; ++ds) {
;         const int ad = C1 ? sub1(kaddr[ds]) : kaddr[ds];
;         const bf16x8 a0 = *(const ATT_LAS bf16x8*)(kb + ad);
;         const bf16x8 qv = *(const ATT_LAS bf16x8*)(qb_ + ad);
;         s0 = ATT_MFMA(a0, qv, s0);
;     }
; }
; __device__ __forceinline__ void attn_unit(ATT_LAS unsigned char* lds, const bf16_t* Qg, const bf16_t* Kg, const bf16_t* Vg, bf16_t* Og, int b, int head, int qb, float lam, const float* subg) {
;     ...
;     for (int t = 0; t < NT; ++t) {
;         const int buf = t & 1;
;         if (t + 1 < NT) ATT_STAGE(t + 1, buf ^ 1);
;         const int kvrel = 64 * t - q0 - 32 * wq;
;         if (kvrel <= 31) {
;             const ATT_LAS unsigned char* kb = lds + KBUF + buf * 16384;
;             const ATT_LAS unsigned char* vb = lds + VBUF + buf * 16384;
;             tile_body(kvrel + 63 > 0, kb, vb, qbase, kaddr, vaddr, O1, O2, m1, m2, l1, l2, kvrel, r, h, wsf);
.Lhead_p1:
	s_add_i32 s79, s79, 1
	s_mov_b32 m0, s77
	s_cmp_ge_u32 s79, s76
	s_cbranch_scc1 .Lq_prefetch_p1
	global_load_lds_dwordx4 v198, s[92:93]
.Ltile_p1:
	s_cmp_gt_i32 s80, 31
	s_cbranch_scc1 .Ldma_skip
.Lbody_p1:
	ds_read_b128 v[2:5], v203 offset:16384
	ds_read_b128 v[6:9], v217
	ds_read_b128 v[10:13], v204 offset:16384
	ds_read_b128 v[146:149], v219
	ds_read_b128 v[150:153], v205 offset:16384
	ds_read_b128 v[154:157], v221
	ds_read_b128 v[158:161], v206 offset:16384
	ds_read_b128 v[162:165], v223
	s_cmpk_gt_i32 s80, 0xffc1
	s_cselect_b64 s[36:37], -1, 0
	s_cmpk_lt_i32 s80, 0xffc2
	s_waitcnt lgkmcnt(4)
	v_mfma_f32_32x32x16_bf16 v[170:185], v[2:5], v[6:9], 0
	v_mfma_f32_32x32x16_bf16 v[170:185], v[10:13], v[146:149], v[170:185]
	s_waitcnt lgkmcnt(0)
	v_mfma_f32_32x32x16_bf16 v[170:185], v[150:153], v[154:157], v[170:185]
	v_mfma_f32_32x32x16_bf16 v[170:185], v[158:161], v[162:165], v[170:185]
	s_cbranch_scc0 .Lhead_mask_p1

; __device__ __forceinline__ void tile_body(bool MASK, const ATT_LAS unsigned char* kb, const ATT_LAS unsigned char* vb, const ATT_LAS unsigned char* qbase, const int (&kaddr)[4], const int (&vaddr)[2], ...
;     ...
;     apply_mask(MASK, Sa, kvrel, r, h); ls = l1;
;     sm = step_fused<false, true, true>(Sa, m1, l1, pkA, O1, pkA, vb, vaddr, Sb, kb, qbase, kaddr);
;     if (__any(!(sm <= GUARD))) slow_step<false>(MASK, Sa, kb, qbase, kaddr, vaddr, O1, m1, l1, ls, kvrel, r, h, wsf, pkA);
.Lpfix_slow_1_p0:
	s_mov_b32 s81, 0x0
	s_branch .Lfix_slow_1

; __device__ __forceinline__ void tile_body(bool MASK, const ATT_LAS unsigned char* kb, const ATT_LAS unsigned char* vb, const ATT_LAS unsigned char* qbase, const int (&kaddr)[4], const int (&vaddr)[2], ...
;     ...
;     apply_mask(MASK, Sa, kvrel, r, h); ls = l1;
;     sm = step_fused<false, true, true>(Sa, m1, l1, pkA, O1, pkA, vb, vaddr, Sb, kb, qbase, kaddr);
;     if (__any(!(sm <= GUARD))) slow_step<false>(MASK, Sa, kb, qbase, kaddr, vaddr, O1, m1, l1, ls, kvrel, r, h, wsf, pkA);
.Lpfix_slow_1_p1:
	s_mov_b32 s81, 0x4000
	s_branch .Lfix_slow_1
